# grid barrier: non-leader workgroups poll the cross-XCD release word directly (same generation value) instead of waiting for the per-XCD re-publish hop
# baseline (speedup 1.0000x reference)
; __device__ __forceinline__ unsigned xb_ld(unsigned* p)              { return __hip_atomic_load(p, __ATOMIC_RELAXED, __HIP_MEMORY_SCOPE_AGENT); }
; __device__ __forceinline__ unsigned xb_add(unsigned* p, unsigned v) { return __hip_atomic_fetch_add(p, v, __ATOMIC_RELAXED, __HIP_MEMORY_SCOPE_AGENT); }
; #define XB_SPIN(cond, bar) do { unsigned _sp = 0; while (cond) { __builtin_amdgcn_s_sleep(6); \
;     if ((++_sp & 255u) == 0u) { if (xb_ld(&(bar)[XB_TMO])) break; if (_sp > XB_SPIN_CAP) { atomicAdd(&(bar)[XB_TMO], 1u); break; } } } } while (0)
; __device__ __forceinline__ void xcd_barrier(const XcdBarrier& b) {
;     ...
;         const unsigned old = xb_add(&bar[XB_XSUB(b.x)], 1u);
;         const unsigned gen = old / nloc;
;         if (old + 1u == (gen + 1u) * nloc) {
;             __builtin_amdgcn_fence(__ATOMIC_RELEASE, "agent");
;             asm volatile("s_waitcnt vmcnt(0)" ::: "memory");
;             const unsigned og = xb_add(&bar[XB_TOP], 1u);
;             const unsigned tg = og / nx;
;             if (og + 1u == (tg + 1u) * nx) xb_add(&bar[XB_TOPGEN], 1u);
;             else XB_SPIN(xb_ld(&bar[XB_TOPGEN]) == tg, bar);
;             __builtin_amdgcn_fence(__ATOMIC_ACQUIRE, "agent");
;             xb_add(&bar[XB_XGEN(b.x)], 1u);
;             asm volatile("s_waitcnt vmcnt(0)" ::: "memory");
;         } else {
;             XB_SPIN(xb_ld(&bar[XB_XGEN(b.x)]) == gen, bar);
;             __builtin_amdgcn_fence(__ATOMIC_ACQUIRE, "agent");
;             asm volatile("s_waitcnt vmcnt(0)" ::: "memory");
.LBB0_104:
	s_lshl_b32 s4, s13, 8
	s_mov_b32 s5, 0
	v_lshl_add_u64 v[2:3], v[0:1], 0, s[4:5]
	v_add_co_u32_e32 v8, vcc, 0x28d01000, v2
	v_mov_b32_e32 v5, 1
	s_nop 0
	v_addc_co_u32_e32 v9, vcc, 0, v3, vcc
	global_atomic_add v5, v[8:9], v5, off offset:1024 sc0
	v_cvt_f32_u32_e32 v7, v6
	v_sub_u32_e32 v8, 0, v6
	s_mov_b64 s[4:5], 0x28d00000
	v_lshl_add_u64 v[2:3], v[2:3], 0, s[4:5]
	v_rcp_iflag_f32_e32 v7, v7
	s_nop 0
	v_mul_f32_e32 v7, 0x4f7ffffe, v7
	v_cvt_u32_f32_e32 v7, v7
	v_mul_lo_u32 v8, v8, v7
	v_mul_hi_u32 v8, v7, v8
	v_add_u32_e32 v7, v7, v8
	s_waitcnt vmcnt(0)
	v_mul_hi_u32 v7, v5, v7
	v_mul_lo_u32 v9, v7, v6
	v_add_u32_e32 v8, 1, v5
	v_sub_u32_e32 v5, v5, v9
	v_add_u32_e32 v10, 1, v7
	v_cmp_ge_u32_e32 vcc, v5, v6
	v_sub_u32_e32 v9, v5, v6
	s_nop 0
	v_cndmask_b32_e32 v7, v7, v10, vcc
	v_cndmask_b32_e32 v5, v5, v9, vcc
	v_add_u32_e32 v9, 1, v7
	v_cmp_ge_u32_e32 vcc, v5, v6
	s_nop 1
	v_cndmask_b32_e32 v5, v7, v9, vcc
	v_mad_u64_u32 v[6:7], s[4:5], v6, v5, v[6:7]
	v_cmp_ne_u32_e32 vcc, v8, v6
	s_and_saveexec_b64 s[4:5], vcc
	s_xor_b64 s[4:5], exec, s[4:5]
	s_cbranch_execz .LBB0_117
	s_mov_b64 s[8:9], 0x28d03500
	v_lshl_add_u64 v[6:7], v[0:1], 0, s[8:9]
	s_waitcnt lgkmcnt(0)
	global_load_dword v4, v[6:7], off sc1
	s_waitcnt vmcnt(0)
	v_cmp_eq_u32_e32 vcc, v4, v5
	s_and_saveexec_b64 s[6:7], vcc
	s_cbranch_execz .LBB0_116
	v_mov_b64_e32 v[2:3], v[6:7]
	s_mov_b64 s[8:9], 0x28d00200
	v_lshl_add_u64 v[0:1], v[0:1], 0, s[8:9]
	s_mov_b32 s13, 1
	s_mov_b64 s[8:9], 0
	s_branch .LBB0_108

; __device__ __forceinline__ unsigned xb_ld(unsigned* p)              { return __hip_atomic_load(p, __ATOMIC_RELAXED, __HIP_MEMORY_SCOPE_AGENT); }
; __device__ __forceinline__ unsigned xb_add(unsigned* p, unsigned v) { return __hip_atomic_fetch_add(p, v, __ATOMIC_RELAXED, __HIP_MEMORY_SCOPE_AGENT); }
; #define XB_SPIN(cond, bar) do { unsigned _sp = 0; while (cond) { __builtin_amdgcn_s_sleep(6); \
;     if ((++_sp & 255u) == 0u) { if (xb_ld(&(bar)[XB_TMO])) break; if (_sp > XB_SPIN_CAP) { atomicAdd(&(bar)[XB_TMO], 1u); break; } } } } while (0)
; __device__ __forceinline__ void xcd_barrier(const XcdBarrier& b) {
;     ...
;         const unsigned old = xb_add(&bar[XB_XSUB(b.x)], 1u);
;         const unsigned gen = old / nloc;
;         if (old + 1u == (gen + 1u) * nloc) {
;             __builtin_amdgcn_fence(__ATOMIC_RELEASE, "agent");
;             asm volatile("s_waitcnt vmcnt(0)" ::: "memory");
;             const unsigned og = xb_add(&bar[XB_TOP], 1u);
;             const unsigned tg = og / nx;
;             if (og + 1u == (tg + 1u) * nx) xb_add(&bar[XB_TOPGEN], 1u);
;             else XB_SPIN(xb_ld(&bar[XB_TOPGEN]) == tg, bar);
;             __builtin_amdgcn_fence(__ATOMIC_ACQUIRE, "agent");
;             xb_add(&bar[XB_XGEN(b.x)], 1u);
;             asm volatile("s_waitcnt vmcnt(0)" ::: "memory");
;         } else {
;             XB_SPIN(xb_ld(&bar[XB_XGEN(b.x)]) == gen, bar);
;             __builtin_amdgcn_fence(__ATOMIC_ACQUIRE, "agent");
;             asm volatile("s_waitcnt vmcnt(0)" ::: "memory");
.LBB0_294:
	s_lshl_b32 s38, s38, 8
	v_lshl_add_u64 v[2:3], v[0:1], 0, s[38:39]
	v_add_co_u32_e32 v8, vcc, 0x28d01000, v2
	v_cvt_f32_u32_e32 v7, v6
	s_nop 0
	v_addc_co_u32_e32 v9, vcc, 0, v3, vcc
	global_atomic_add v5, v[8:9], v195, off offset:1024 sc0
	v_rcp_iflag_f32_e32 v7, v7
	v_sub_u32_e32 v8, 0, v6
	s_mov_b64 s[4:5], 0x28d00000
	v_lshl_add_u64 v[2:3], v[2:3], 0, s[4:5]
	v_mul_f32_e32 v7, 0x4f7ffffe, v7
	v_cvt_u32_f32_e32 v7, v7
	v_mul_lo_u32 v8, v8, v7
	v_mul_hi_u32 v8, v7, v8
	v_add_u32_e32 v7, v7, v8
	s_waitcnt vmcnt(0)
	v_mul_hi_u32 v7, v5, v7
	v_mul_lo_u32 v9, v7, v6
	v_add_u32_e32 v8, 1, v5
	v_sub_u32_e32 v5, v5, v9
	v_add_u32_e32 v10, 1, v7
	v_cmp_ge_u32_e32 vcc, v5, v6
	v_sub_u32_e32 v9, v5, v6
	s_nop 0
	v_cndmask_b32_e32 v7, v7, v10, vcc
	v_cndmask_b32_e32 v5, v5, v9, vcc
	v_add_u32_e32 v9, 1, v7
	v_cmp_ge_u32_e32 vcc, v5, v6
	s_nop 1
	v_cndmask_b32_e32 v5, v7, v9, vcc
	v_mad_u64_u32 v[6:7], s[4:5], v6, v5, v[6:7]
	v_cmp_ne_u32_e32 vcc, v8, v6
	s_and_saveexec_b64 s[4:5], vcc
	s_xor_b64 s[4:5], exec, s[4:5]
	s_cbranch_execz .LBB0_307
	s_mov_b64 s[8:9], 0x28d03500
	v_lshl_add_u64 v[6:7], v[0:1], 0, s[8:9]
	s_waitcnt lgkmcnt(0)
	global_load_dword v4, v[6:7], off sc1
	s_waitcnt vmcnt(0)
	v_cmp_eq_u32_e32 vcc, v4, v5
	s_and_saveexec_b64 s[6:7], vcc
	s_cbranch_execz .LBB0_306
	v_mov_b64_e32 v[2:3], v[6:7]
	s_mov_b64 s[8:9], 0x28d00200
	v_lshl_add_u64 v[0:1], v[0:1], 0, s[8:9]
	s_mov_b32 s24, 1
	s_mov_b64 s[8:9], 0
	s_branch .LBB0_298
